# P8 residual epilogue (32 serial round trips): touch-prefetch of the whole residual tile at the epilogue top, on top of v71
# baseline (speedup 1.0000x reference)
.LBB0_1733:
	v_lshl_add_u32 v138, s55, 8, v140
	v_lshl_or_b32 v134, s54, 8, v142
	v_ashrrev_i32_e32 v139, 31, v138
	v_ashrrev_i32_e32 v135, 31, v134
	v_lshlrev_b64 v[136:137], 14, v[138:139]
	v_lshl_add_u64 v[146:147], s[6:7], 0, v[136:137]
	v_lshlrev_b64 v[136:137], 2, v[134:135]
	v_lshl_add_u64 v[134:135], v[146:147], 0, v[136:137]
	v_mov_b32_e32 v245, 0
	global_load_dword v249, v[134:135], off offset:512
	v_mov_b32_e32 v244, 0x40000
	v_lshl_add_u64 v[246:247], v[244:245], 0, v[134:135]
	global_load_dword v249, v[246:247], off
	global_load_dword v249, v[246:247], off offset:512
	v_mov_b32_e32 v244, 0x80000
	v_lshl_add_u64 v[246:247], v[244:245], 0, v[134:135]
	global_load_dword v249, v[246:247], off
	global_load_dword v249, v[246:247], off offset:512
	v_mov_b32_e32 v244, 0xc0000
	v_lshl_add_u64 v[246:247], v[244:245], 0, v[134:135]
	global_load_dword v249, v[246:247], off
	global_load_dword v249, v[246:247], off offset:512
	v_mov_b32_e32 v244, 0x200000
	v_lshl_add_u64 v[246:247], v[244:245], 0, v[134:135]
	global_load_dword v249, v[246:247], off
	global_load_dword v249, v[246:247], off offset:512
	v_mov_b32_e32 v244, 0x240000
	v_lshl_add_u64 v[246:247], v[244:245], 0, v[134:135]
	global_load_dword v249, v[246:247], off
	global_load_dword v249, v[246:247], off offset:512
	v_mov_b32_e32 v244, 0x280000
	v_lshl_add_u64 v[246:247], v[244:245], 0, v[134:135]
	global_load_dword v249, v[246:247], off
	global_load_dword v249, v[246:247], off offset:512
	v_mov_b32_e32 v244, 0x2c0000
	v_lshl_add_u64 v[246:247], v[244:245], 0, v[134:135]
	global_load_dword v249, v[246:247], off
	global_load_dword v249, v[246:247], off offset:512
	global_load_dwordx4 v[146:149], v[134:135], off
	s_mov_b64 s[2:3], -1
	s_waitcnt vmcnt(0)
	v_pk_add_f32 v[128:129], v[128:129], v[148:149]
	v_pk_add_f32 v[126:127], v[126:127], v[146:147]
	global_store_dwordx4 v[134:135], v[126:129], off
	global_load_dwordx4 v[126:129], v[134:135], off offset:64
	s_waitcnt vmcnt(0)
	v_pk_add_f32 v[124:125], v[124:125], v[128:129]
	v_pk_add_f32 v[122:123], v[122:123], v[126:127]
	global_store_dwordx4 v[134:135], v[122:125], off offset:64
	global_load_dwordx4 v[122:125], v[134:135], off offset:512
	s_waitcnt vmcnt(0)
	v_pk_add_f32 v[120:121], v[120:121], v[124:125]
	v_pk_add_f32 v[118:119], v[118:119], v[122:123]
	global_store_dwordx4 v[134:135], v[118:121], off offset:512
	global_load_dwordx4 v[118:121], v[134:135], off offset:576
	s_waitcnt vmcnt(0)
	v_pk_add_f32 v[112:113], v[112:113], v[120:121]
	v_pk_add_f32 v[110:111], v[110:111], v[118:119]
	global_store_dwordx4 v[134:135], v[110:113], off offset:576
	s_nop 1
	v_or_b32_e32 v110, 16, v138
	v_ashrrev_i32_e32 v111, 31, v110
	v_lshlrev_b64 v[110:111], 14, v[110:111]
	v_lshl_add_u64 v[110:111], s[6:7], 0, v[110:111]
	v_lshl_add_u64 v[118:119], v[110:111], 0, v[136:137]
	global_load_dwordx4 v[110:113], v[118:119], off
	s_waitcnt vmcnt(0)
	v_pk_add_f32 v[112:113], v[116:117], v[112:113]
	v_pk_add_f32 v[110:111], v[114:115], v[110:111]
	global_store_dwordx4 v[118:119], v[110:113], off
	global_load_dwordx4 v[110:113], v[118:119], off offset:64
	s_waitcnt vmcnt(0)
	v_pk_add_f32 v[108:109], v[108:109], v[112:113]
	v_pk_add_f32 v[106:107], v[106:107], v[110:111]
	global_store_dwordx4 v[118:119], v[106:109], off offset:64
	global_load_dwordx4 v[106:109], v[118:119], off offset:512
	s_waitcnt vmcnt(0)
	v_pk_add_f32 v[104:105], v[104:105], v[108:109]
	v_pk_add_f32 v[102:103], v[102:103], v[106:107]
	global_store_dwordx4 v[118:119], v[102:105], off offset:512
	global_load_dwordx4 v[102:105], v[118:119], off offset:576
	s_waitcnt vmcnt(0)
	v_pk_add_f32 v[100:101], v[100:101], v[104:105]
	v_pk_add_f32 v[98:99], v[98:99], v[102:103]
	global_store_dwordx4 v[118:119], v[98:101], off offset:576
	s_nop 1
	v_or_b32_e32 v98, 32, v138
	v_ashrrev_i32_e32 v99, 31, v98
	v_lshlrev_b64 v[98:99], 14, v[98:99]
	v_lshl_add_u64 v[98:99], s[6:7], 0, v[98:99]
	v_lshl_add_u64 v[102:103], v[98:99], 0, v[136:137]
	global_load_dwordx4 v[98:101], v[102:103], off
	s_waitcnt vmcnt(0)
	v_pk_add_f32 v[96:97], v[96:97], v[100:101]
	v_pk_add_f32 v[94:95], v[94:95], v[98:99]
	global_store_dwordx4 v[102:103], v[94:97], off
	global_load_dwordx4 v[94:97], v[102:103], off offset:64
	s_waitcnt vmcnt(0)
	v_pk_add_f32 v[92:93], v[92:93], v[96:97]
	v_pk_add_f32 v[90:91], v[90:91], v[94:95]
	global_store_dwordx4 v[102:103], v[90:93], off offset:64
	global_load_dwordx4 v[90:93], v[102:103], off offset:512
	s_waitcnt vmcnt(0)
	v_pk_add_f32 v[88:89], v[88:89], v[92:93]
	v_pk_add_f32 v[86:87], v[86:87], v[90:91]
	global_store_dwordx4 v[102:103], v[86:89], off offset:512
	global_load_dwordx4 v[86:89], v[102:103], off offset:576
	s_waitcnt vmcnt(0)
	v_pk_add_f32 v[84:85], v[84:85], v[88:89]
	v_pk_add_f32 v[82:83], v[82:83], v[86:87]
	global_store_dwordx4 v[102:103], v[82:85], off offset:576
	s_nop 1
	v_or_b32_e32 v82, 48, v138
	v_ashrrev_i32_e32 v83, 31, v82
	v_lshlrev_b64 v[82:83], 14, v[82:83]
	v_lshl_add_u64 v[82:83], s[6:7], 0, v[82:83]
	v_lshl_add_u64 v[86:87], v[82:83], 0, v[136:137]
	global_load_dwordx4 v[82:85], v[86:87], off
	s_waitcnt vmcnt(0)
	v_pk_add_f32 v[80:81], v[80:81], v[84:85]
	v_pk_add_f32 v[78:79], v[78:79], v[82:83]
	global_store_dwordx4 v[86:87], v[78:81], off
	global_load_dwordx4 v[78:81], v[86:87], off offset:64
	s_waitcnt vmcnt(0)
	v_pk_add_f32 v[76:77], v[76:77], v[80:81]
	v_pk_add_f32 v[74:75], v[74:75], v[78:79]
	global_store_dwordx4 v[86:87], v[74:77], off offset:64
	global_load_dwordx4 v[74:77], v[86:87], off offset:512
	s_waitcnt vmcnt(0)
	v_pk_add_f32 v[72:73], v[72:73], v[76:77]
	v_pk_add_f32 v[70:71], v[70:71], v[74:75]
	global_store_dwordx4 v[86:87], v[70:73], off offset:512
	global_load_dwordx4 v[70:73], v[86:87], off offset:576
	s_waitcnt vmcnt(0)
	v_pk_add_f32 v[68:69], v[68:69], v[72:73]
	v_add_co_u32_e32 v72, vcc, s48, v134
	v_pk_add_f32 v[66:67], v[66:67], v[70:71]
	s_nop 0
	v_addc_co_u32_e32 v73, vcc, 0, v135, vcc
	global_store_dwordx4 v[86:87], v[66:69], off offset:576
	global_load_dwordx4 v[66:69], v[72:73], off
	v_lshl_add_u64 v[70:71], v[134:135], 0, s[12:13]
	s_waitcnt vmcnt(0)
	v_pk_add_f32 v[64:65], v[64:65], v[68:69]
	v_pk_add_f32 v[62:63], v[62:63], v[66:67]
	global_store_dwordx4 v[72:73], v[62:65], off
	global_load_dwordx4 v[62:65], v[70:71], off offset:64
	s_waitcnt vmcnt(0)
	v_pk_add_f32 v[60:61], v[60:61], v[64:65]
	v_pk_add_f32 v[58:59], v[58:59], v[62:63]
	global_store_dwordx4 v[70:71], v[58:61], off offset:64
	global_load_dwordx4 v[58:61], v[70:71], off offset:512
	s_waitcnt vmcnt(0)
	v_pk_add_f32 v[56:57], v[56:57], v[60:61]
	v_pk_add_f32 v[54:55], v[54:55], v[58:59]
	global_store_dwordx4 v[70:71], v[54:57], off offset:512
	global_load_dwordx4 v[54:57], v[70:71], off offset:576
	s_waitcnt vmcnt(0)
	v_pk_add_f32 v[52:53], v[52:53], v[56:57]
	v_add_co_u32_e32 v56, vcc, s49, v134
	v_pk_add_f32 v[50:51], v[50:51], v[54:55]
	s_nop 0
	v_addc_co_u32_e32 v57, vcc, 0, v135, vcc
	global_store_dwordx4 v[70:71], v[50:53], off offset:576
	global_load_dwordx4 v[50:53], v[56:57], off
	v_lshl_add_u64 v[54:55], v[134:135], 0, s[14:15]
	s_waitcnt vmcnt(0)
	v_pk_add_f32 v[48:49], v[48:49], v[52:53]
	v_pk_add_f32 v[46:47], v[46:47], v[50:51]
	global_store_dwordx4 v[56:57], v[46:49], off
	global_load_dwordx4 v[46:49], v[54:55], off offset:64
	s_waitcnt vmcnt(0)
	v_pk_add_f32 v[44:45], v[44:45], v[48:49]
	v_pk_add_f32 v[42:43], v[42:43], v[46:47]
	global_store_dwordx4 v[54:55], v[42:45], off offset:64
	global_load_dwordx4 v[42:45], v[54:55], off offset:512
	s_waitcnt vmcnt(0)
	v_pk_add_f32 v[40:41], v[40:41], v[44:45]
	v_pk_add_f32 v[38:39], v[38:39], v[42:43]
	global_store_dwordx4 v[54:55], v[38:41], off offset:512
	global_load_dwordx4 v[38:41], v[54:55], off offset:576
	s_waitcnt vmcnt(0)
	v_pk_add_f32 v[36:37], v[36:37], v[40:41]
	v_add_co_u32_e32 v40, vcc, s50, v134
	v_pk_add_f32 v[34:35], v[34:35], v[38:39]
	s_nop 0
	v_addc_co_u32_e32 v41, vcc, 0, v135, vcc
	global_store_dwordx4 v[54:55], v[34:37], off offset:576
	global_load_dwordx4 v[34:37], v[40:41], off
	v_lshl_add_u64 v[38:39], v[134:135], 0, s[16:17]
	s_waitcnt vmcnt(0)
	v_pk_add_f32 v[32:33], v[32:33], v[36:37]
	v_pk_add_f32 v[30:31], v[30:31], v[34:35]
	global_store_dwordx4 v[40:41], v[30:33], off
	global_load_dwordx4 v[30:33], v[38:39], off offset:64
	s_waitcnt vmcnt(0)
	v_pk_add_f32 v[28:29], v[28:29], v[32:33]
	v_pk_add_f32 v[26:27], v[26:27], v[30:31]
	global_store_dwordx4 v[38:39], v[26:29], off offset:64
	global_load_dwordx4 v[26:29], v[38:39], off offset:512
	s_waitcnt vmcnt(0)
	v_pk_add_f32 v[24:25], v[24:25], v[28:29]
	v_pk_add_f32 v[22:23], v[22:23], v[26:27]
	global_store_dwordx4 v[38:39], v[22:25], off offset:512
	global_load_dwordx4 v[22:25], v[38:39], off offset:576
	s_waitcnt vmcnt(0)
	v_pk_add_f32 v[20:21], v[20:21], v[24:25]
	v_add_co_u32_e32 v24, vcc, s51, v134
	v_pk_add_f32 v[18:19], v[18:19], v[22:23]
	s_nop 0
	v_addc_co_u32_e32 v25, vcc, 0, v135, vcc
	global_store_dwordx4 v[38:39], v[18:21], off offset:576
	global_load_dwordx4 v[20:23], v[24:25], off
	s_and_b64 vcc, exec, s[0:1]
	v_lshl_add_u64 v[18:19], v[134:135], 0, s[18:19]
	s_waitcnt vmcnt(0)
	v_pk_add_f32 v[16:17], v[16:17], v[22:23]
	v_pk_add_f32 v[14:15], v[14:15], v[20:21]
	global_store_dwordx4 v[24:25], v[14:17], off
	global_load_dwordx4 v[14:17], v[18:19], off offset:64
	s_waitcnt vmcnt(0)
	v_pk_add_f32 v[12:13], v[12:13], v[16:17]
	v_pk_add_f32 v[10:11], v[10:11], v[14:15]
	global_store_dwordx4 v[18:19], v[10:13], off offset:64
	global_load_dwordx4 v[10:13], v[18:19], off offset:512
	s_waitcnt vmcnt(0)
	v_pk_add_f32 v[8:9], v[8:9], v[12:13]
	v_pk_add_f32 v[6:7], v[6:7], v[10:11]
	global_store_dwordx4 v[18:19], v[6:9], off offset:512
	global_load_dwordx4 v[6:9], v[18:19], off offset:576
	s_waitcnt vmcnt(0)
	v_pk_add_f32 v[4:5], v[4:5], v[8:9]
	v_pk_add_f32 v[2:3], v[2:3], v[6:7]
	global_store_dwordx4 v[18:19], v[2:5], off offset:576
	s_cbranch_vccnz .LBB0_1716
	s_andn2_b64 vcc, exec, s[4:5]
	s_cbranch_vccnz .LBB0_1715
	s_barrier
	s_branch .LBB0_1715
